# retention scan loop: counted vmcnt(7)/(5) instead of vmcnt(0) at loop head
# baseline (speedup 1.0000x reference)
.LBB0_1368:
	s_cmp_lt_i32 s14, 0
	s_cselect_b64 s[4:5], -1, 0
	s_and_b64 vcc, exec, s[4:5]
	s_cbranch_vccnz .LBB0_1355
	v_sub_co_u32_e64 v0, s[36:37], s14, 64
	s_xor_b64 s[6:7], s[36:37], -1
	s_and_b64 s[0:1], s[36:37], exec
	v_readfirstlane_b32 s0, v0
	s_cselect_b32 s18, s14, s0
	s_cselect_b32 s55, s48, 0x100
	s_ashr_i32 s14, s18, 4
	s_lshl_b32 s15, s14, 10
	s_bfe_u32 s1, s18, 0x30001
	s_and_b32 s0, s18, 1
	s_add_i32 s38, s15, 0x2000
	s_lshl_b32 s39, s14, 8
	s_and_b64 s[14:15], s[36:37], exec
	s_cselect_b32 s56, s38, s39
	s_lshl_b32 s15, s0, 3
	s_and_b32 s14, s18, -16
	s_or_b32 s18, s15, s1
	s_or_b32 s14, s18, s14
	s_ashr_i32 s15, s14, 31
	s_lshl_b64 s[14:15], s[14:15], 16
	s_add_u32 s38, s44, s14
	s_addc_u32 s39, s45, s15
	s_and_b64 s[36:37], s[36:37], exec
	s_cselect_b32 s43, s39, 0
	s_cselect_b32 s42, s38, 0
	s_lshl_b32 s18, s18, 2
	v_readlane_b32 s76, v254, 0
	v_mov_b32_e32 v0, s18
	v_readlane_b32 s78, v254, 2
	v_readlane_b32 s79, v254, 3
	v_mov_b32_e32 v1, v224
	v_mov_b32_e32 v127, v2
	v_mov_b32_e32 v125, v2
	v_mov_b32_e32 v123, v2
	v_mov_b32_e32 v119, v2
	global_load_dword v4, v0, s[78:79]
	v_mov_b32_e32 v117, v2
	v_bfe_u32 v3, v1, 4, 2
	v_lshlrev_b32_e32 v49, 2, v3
	s_waitcnt vmcnt(4)
	v_or_b32_e32 v9, 3, v49
	v_lshlrev_b32_e32 v10, 8, v9
	v_and_b32_e32 v10, 0xe00, v10
	v_or_b32_e32 v82, 0x4000, v10
	v_ashrrev_i32_e32 v174, 4, v1
	s_waitcnt vmcnt(3)
	v_ashrrev_i32_e32 v5, 2, v1
	v_lshlrev_b32_e32 v6, 6, v1
	v_sub_u32_e32 v7, s55, v174
	v_and_b32_e32 v0, -16, v5
	v_bfi_b32 v112, -16, v5, v1
	v_and_b32_e32 v5, 0xc00, v6
	v_add_u32_e32 v6, 32, v174
	v_subrev_u32_e32 v7, 33, v7
	v_and_b32_e32 v173, 15, v1
	v_or_b32_e32 v102, 0x7000, v5
	v_or_b32_e32 v104, 0x3200, v5
	v_or_b32_e32 v106, 0x7200, v5
	v_or_b32_e32 v116, 0xf000, v5
	v_or_b32_e32 v114, 0xb200, v5
	v_or_b32_e32 v140, 0xf200, v5
	v_or_b32_e32 v8, 2, v49
	v_lshlrev_b32_e32 v80, 8, v8
	v_lshlrev_b32_e32 v76, 10, v3
	v_ashrrev_i32_e32 v113, 31, v112
	v_or_b32_e32 v126, 0xa000, v76
	v_or_b32_e32 v124, 0xe000, v76
	v_or_b32_e32 v122, 0xa200, v76
	v_or_b32_e32 v118, 0xb000, v76
	v_mov_b32_e32 v115, v2
	v_mov_b32_e32 v141, v2
	v_mov_b32_e32 v109, v2
	v_mov_b32_e32 v111, v2
	v_or_b32_e32 v108, 0x8000, v76
	v_or_b32_e32 v110, 0xc000, v76
	v_or_b32_e32 v138, 0x8200, v76
	v_mov_b32_e32 v139, v2
	v_or_b32_e32 v134, 0x9000, v76
	v_mov_b32_e32 v135, v2
	v_or_b32_e32 v132, 0xd000, v76
	v_mov_b32_e32 v133, v2
	v_or_b32_e32 v130, 0x9200, v76
	v_mov_b32_e32 v131, v2
	v_or_b32_e32 v128, 0xd200, v76
	v_mov_b32_e32 v129, v2
	v_or_b32_e32 v120, 0xe200, v76
	v_mov_b32_e32 v121, v2
	v_mov_b32_e32 v93, v2
	v_mov_b32_e32 v95, v2
	v_mov_b32_e32 v97, v2
	v_mov_b32_e32 v101, v2
	v_mov_b32_e32 v103, v2
	v_mov_b32_e32 v105, v2
	v_mov_b32_e32 v107, v2
	v_or_b32_e32 v92, 0x2000, v76
	v_or_b32_e32 v94, 0x6000, v76
	v_or_b32_e32 v96, 0x2200, v76
	v_or_b32_e32 v100, 0x3000, v76
	v_or_b32_e32 v136, 0xc200, v76
	v_mov_b32_e32 v137, v2
	v_mov_b32_e32 v77, v2
	v_mov_b32_e32 v79, v2
	v_mov_b32_e32 v81, v2
	v_mov_b32_e32 v83, v2
	v_mov_b32_e32 v85, v2
	v_mov_b32_e32 v87, v2
	v_mov_b32_e32 v89, v2
	v_mov_b32_e32 v91, v2
	v_mov_b32_e32 v99, v2
	v_or_b32_e32 v78, 0x4000, v76
	v_or_b32_e32 v84, 0x1000, v76
	v_or_b32_e32 v86, 0x5000, v76
	v_or_b32_e32 v88, 0x1200, v76
	v_or_b32_e32 v90, 0x5200, v76
	v_or_b32_e32 v98, 0x6200, v76
	v_xor_b32_e32 v23, 28, v49
	s_waitcnt vmcnt(0)
	v_mul_f32_e64 v11, |v4|, s49
	v_exp_f32_e32 v11, v11
	v_max_f32_e32 v4, v4, v4
	v_min_f32_e32 v4, 0, v4
	v_lshlrev_b32_e32 v48, 3, v1
	v_add_f32_e32 v10, 1.0, v11
	v_cmp_gt_f32_e32 vcc, s50, v10
	s_and_b64 s[36:37], vcc, exec
	s_cselect_b32 s18, 32, 0
	s_lshl_b32 s46, s1, 8
	s_add_u32 s36, s60, s46
	v_ldexp_f32 v10, v10, s18
	s_addc_u32 s37, s61, 0
	v_log_f32_e32 v10, v10
	s_add_u32 s38, s17, s46
	s_addc_u32 s39, s19, 0
	s_add_u32 s40, s88, s46
	s_addc_u32 s41, s89, 0
	v_mul_f32_e32 v12, 0x3f317217, v10
	s_cmp_eq_u32 s0, 0
	v_cndmask_b32_e32 v11, 0, v172, vcc
	v_fma_f32 v12, v10, s51, -v12
	s_cselect_b64 vcc, -1, 0
	v_fmac_f32_e32 v12, 0x3377d1cf, v10
	s_and_b64 s[0:1], vcc, exec
	v_fmac_f32_e32 v12, 0x3f317217, v10
	v_cmp_lt_f32_e64 s[0:1], |v10|, s52
	v_cndmask_b32_e32 v22, v7, v6, vcc
	v_sub_u32_e32 v7, v173, v9
	v_cndmask_b32_e64 v6, v10, v12, s[0:1]
	v_sub_f32_e32 v6, v6, v11
	v_sub_f32_e32 v51, v4, v6
	v_sub_u32_e32 v4, v173, v49
	v_cvt_f32_u32_e32 v6, v4
	s_cselect_b32 s0, s53, 0xd522000
	s_add_u32 s0, s24, s0
	s_addc_u32 s1, s25, 0
	v_mul_f32_e32 v5, v51, v6
	v_add_u32_e32 v6, 16, v4
	v_cvt_f32_u32_e32 v6, v6
	v_mul_f32_e32 v5, 0x3fb8aa3b, v5
	s_add_u32 s46, s0, s46
	v_exp_f32_e32 v5, v5
	v_mul_f32_e32 v6, v51, v6
	s_addc_u32 s47, s1, 0
	v_cmp_lt_i32_e64 s[0:1], -1, v4
	v_xad_u32 v4, v49, -1, v173
	v_mul_f32_e32 v6, 0x3fb8aa3b, v6
	v_exp_f32_e32 v144, v6
	v_add_u32_e32 v6, 16, v4
	v_cvt_f32_u32_e32 v6, v6
	v_cndmask_b32_e64 v142, 0, v5, s[0:1]
	v_cvt_f32_u32_e32 v5, v4
	v_cmp_lt_i32_e64 s[0:1], -1, v4
	v_mul_f32_e32 v6, v51, v6
	v_sub_u32_e32 v4, v173, v8
	v_mul_f32_e32 v5, v51, v5
	v_mul_f32_e32 v6, 0x3fb8aa3b, v6
	v_mul_f32_e32 v5, 0x3fb8aa3b, v5
	v_exp_f32_e32 v145, v6
	v_add_u32_e32 v6, 16, v4
	v_exp_f32_e32 v5, v5
	v_cvt_f32_u32_e32 v6, v6
	v_cvt_f32_u32_e32 v8, v7
	s_lshr_b32 s58, s55, 5
	v_cndmask_b32_e64 v143, 0, v5, s[0:1]
	v_cvt_f32_u32_e32 v5, v4
	v_cmp_lt_i32_e64 s[0:1], -1, v4
	v_mul_f32_e32 v4, v51, v6
	v_add_u32_e32 v6, 16, v7
	v_cvt_f32_u32_e32 v6, v6
	v_mul_f32_e32 v5, v51, v5
	v_mul_f32_e32 v4, 0x3fb8aa3b, v4
	v_mul_f32_e32 v5, 0x3fb8aa3b, v5
	v_exp_f32_e32 v148, v4
	v_mul_f32_e32 v4, v51, v6
	v_exp_f32_e32 v5, v5
	v_mul_f32_e32 v4, 0x3fb8aa3b, v4
	v_exp_f32_e32 v149, v4
	v_xor_b32_e32 v4, 31, v49
	v_cvt_f32_ubyte0_e32 v4, v4
	v_mul_f32_e32 v4, v51, v4
	v_cndmask_b32_e64 v146, 0, v5, s[0:1]
	v_mul_f32_e32 v5, v51, v8
	v_mul_f32_e32 v4, 0x3fb8aa3b, v4
	v_mul_f32_e32 v5, 0x3fb8aa3b, v5
	v_exp_f32_e32 v150, v4
	v_xor_b32_e32 v4, 30, v49
	v_exp_f32_e32 v5, v5
	v_cvt_f32_ubyte0_e32 v4, v4
	v_mul_f32_e32 v4, v51, v4
	v_mul_f32_e32 v4, 0x3fb8aa3b, v4
	v_cmp_lt_i32_e64 s[0:1], -1, v7
	v_exp_f32_e32 v151, v4
	v_xor_b32_e32 v4, 29, v49
	s_cmp_eq_u64 s[42:43], 0
	v_cndmask_b32_e64 v147, 0, v5, s[0:1]
	v_cvt_f32_ubyte0_e32 v4, v4
	s_cselect_b64 s[0:1], -1, 0
	v_mul_f32_e32 v4, v51, v4
	s_and_b64 s[62:63], s[0:1], exec
	v_mul_f32_e32 v4, 0x3fb8aa3b, v4
	s_cselect_b32 s18, s45, s43
	s_cselect_b32 s42, s44, s42
	v_exp_f32_e32 v152, v4
	v_mov_b32_e32 v4, s42
	v_mov_b32_e32 v5, s18
	v_lshl_add_u64 v[4:5], v[112:113], 2, v[4:5]
	v_lshl_add_u64 v[6:7], v[4:5], 0, v[118:119]
	v_lshl_add_u64 v[8:9], v[4:5], 0, v[116:117]
	v_lshl_add_u64 v[10:11], v[4:5], 0, v[114:115]
	v_lshl_add_u64 v[12:13], v[4:5], 0, v[140:141]
	v_lshl_add_u64 v[14:15], v[4:5], 0, v[126:127]
	v_lshl_add_u64 v[16:17], v[4:5], 0, v[124:125]
	v_lshl_add_u64 v[18:19], v[4:5], 0, v[122:123]
	v_lshl_add_u64 v[20:21], v[4:5], 0, v[120:121]
	global_load_dword v24, v[6:7], off
	global_load_dword v25, v[8:9], off
	global_load_dword v26, v[10:11], off
	global_load_dword v27, v[12:13], off
	global_load_dword v28, v[14:15], off
	global_load_dword v29, v[16:17], off
	global_load_dword v30, v[18:19], off
	global_load_dword v31, v[20:21], off
	v_lshl_add_u64 v[6:7], v[4:5], 0, v[134:135]
	v_lshl_add_u64 v[8:9], v[4:5], 0, v[132:133]
	v_lshl_add_u64 v[10:11], v[4:5], 0, v[130:131]
	v_lshl_add_u64 v[12:13], v[4:5], 0, v[128:129]
	v_lshl_add_u64 v[14:15], v[4:5], 0, v[108:109]
	v_lshl_add_u64 v[16:17], v[4:5], 0, v[110:111]
	v_lshl_add_u64 v[18:19], v[4:5], 0, v[138:139]
	v_lshl_add_u64 v[20:21], v[4:5], 0, v[136:137]
	global_load_dword v32, v[6:7], off
	global_load_dword v33, v[8:9], off
	global_load_dword v34, v[10:11], off
	global_load_dword v35, v[12:13], off
	global_load_dword v36, v[14:15], off
	global_load_dword v37, v[16:17], off
	global_load_dword v38, v[18:19], off
	global_load_dword v39, v[20:21], off
	v_lshl_add_u64 v[6:7], v[4:5], 0, v[100:101]
	v_lshl_add_u64 v[8:9], v[4:5], 0, v[102:103]
	v_lshl_add_u64 v[10:11], v[4:5], 0, v[104:105]
	v_lshl_add_u64 v[12:13], v[4:5], 0, v[106:107]
	v_lshl_add_u64 v[14:15], v[4:5], 0, v[92:93]
	v_lshl_add_u64 v[16:17], v[4:5], 0, v[94:95]
	v_lshl_add_u64 v[18:19], v[4:5], 0, v[96:97]
	v_lshl_add_u64 v[20:21], v[4:5], 0, v[98:99]
	global_load_dword v40, v[6:7], off
	global_load_dword v41, v[8:9], off
	global_load_dword v42, v[10:11], off
	global_load_dword v43, v[12:13], off
	global_load_dword v44, v[14:15], off
	global_load_dword v45, v[16:17], off
	global_load_dword v46, v[18:19], off
	global_load_dword v47, v[20:21], off
	v_lshl_add_u64 v[6:7], v[4:5], 0, v[84:85]
	v_lshl_add_u64 v[8:9], v[4:5], 0, v[86:87]
	v_lshl_add_u64 v[10:11], v[4:5], 0, v[88:89]
	v_lshl_add_u64 v[12:13], v[4:5], 0, v[90:91]
	v_lshl_add_u64 v[14:15], v[4:5], 0, v[76:77]
	v_lshl_add_u64 v[16:17], v[4:5], 0, v[78:79]
	v_lshl_add_u64 v[18:19], v[4:5], 0, v[80:81]
	v_lshl_add_u64 v[4:5], v[4:5], 0, v[82:83]
	global_load_dword v52, v[6:7], off
	global_load_dword v53, v[8:9], off
	global_load_dword v54, v[10:11], off
	global_load_dword v55, v[12:13], off
	global_load_dword v56, v[14:15], off
	global_load_dword v57, v[16:17], off
	global_load_dword v58, v[18:19], off
	global_load_dword v59, v[4:5], off
	v_cvt_f32_ubyte0_e32 v4, v23
	v_mul_f32_e32 v4, v51, v4
	v_mul_f32_e32 v4, 0x3fb8aa3b, v4
	v_exp_f32_e32 v153, v4
	v_xor_b32_e32 v4, 15, v49
	v_cvt_f32_ubyte0_e32 v4, v4
	v_mul_f32_e32 v4, v51, v4
	v_mul_f32_e32 v4, 0x3fb8aa3b, v4
	v_exp_f32_e32 v154, v4
	v_xor_b32_e32 v4, 14, v49
	v_cvt_f32_ubyte0_e32 v4, v4
	v_mul_f32_e32 v4, v51, v4
	v_mul_f32_e32 v4, 0x3fb8aa3b, v4
	v_exp_f32_e32 v155, v4
	v_xor_b32_e32 v4, 13, v49
	v_cvt_f32_ubyte0_e32 v4, v4
	v_mul_f32_e32 v4, v51, v4
	v_xad_u32 v14, v174, -1, s55
	v_mul_f32_e32 v4, 0x3fb8aa3b, v4
	v_cndmask_b32_e32 v14, v14, v174, vcc
	v_exp_f32_e32 v156, v4
	v_add_u32_e32 v4, s56, v22
	v_add_u32_e32 v14, s56, v14
	v_and_b32_e32 v50, 0x78, v48
	v_ashrrev_i32_e32 v5, 31, v4
	v_ashrrev_i32_e32 v15, 31, v14
	v_lshlrev_b32_e32 v60, 1, v50
	v_lshlrev_b64 v[12:13], 13, v[4:5]
	v_lshlrev_b64 v[16:17], 13, v[14:15]
	v_or_b32_e32 v12, v12, v60
	v_or_b32_e32 v16, v16, v60
	v_lshl_add_u64 v[4:5], s[40:41], 0, v[12:13]
	v_lshl_add_u64 v[8:9], s[38:39], 0, v[12:13]
	v_lshl_add_u64 v[12:13], s[36:37], 0, v[12:13]
	v_lshl_add_u64 v[18:19], s[40:41], 0, v[16:17]
	global_load_dwordx4 v[4:7], v[4:5], off
	s_nop 0
	global_load_dwordx4 v[8:11], v[8:9], off
	s_nop 0
	global_load_dwordx4 v[12:15], v[12:13], off
	s_nop 0
	global_load_dwordx4 v[64:67], v[18:19], off
	v_lshl_add_u64 v[18:19], s[38:39], 0, v[16:17]
	v_lshl_add_u64 v[16:17], s[36:37], 0, v[16:17]
	global_load_dwordx4 v[68:71], v[18:19], off
	global_load_dwordx4 v[72:75], v[16:17], off
	v_xor_b32_e32 v16, 12, v49
	v_cvt_f32_ubyte0_e32 v16, v16
	v_mul_f32_e32 v16, v51, v16
	v_mul_f32_e32 v16, 0x3fb8aa3b, v16
	v_exp_f32_e32 v157, v16
	s_waitcnt vmcnt(37)
	v_cndmask_b32_e64 v16, v24, 0, s[0:1]
	v_bfe_u32 v1, v1, 2, 2
	v_or_b32_e32 v1, v49, v1
	v_mul_u32_u24_e32 v1, 0x88, v1
	v_lshlrev_b32_e32 v49, 1, v1
	v_and_b32_e32 v48, 24, v48
	v_ashrrev_i32_e32 v1, 31, v0
	v_add3_u32 v176, 0, v49, v48
	v_lshlrev_b32_e32 v48, 3, v3
	s_waitcnt vmcnt(29)
	v_cndmask_b32_e64 v24, v32, 0, s[0:1]
	v_mul_u32_u24_e32 v3, 0x88, v173
	v_lshl_add_u32 v177, v0, 1, v176
	v_lshlrev_b32_e32 v3, 1, v3
	v_lshl_add_u64 v[0:1], v[0:1], 1, s[46:47]
	v_mov_b32_e32 v49, v2
	s_mov_b32 s57, 3
	v_cndmask_b32_e64 v17, v25, 0, s[0:1]
	v_cndmask_b32_e64 v18, v26, 0, s[0:1]
	s_waitcnt vmcnt(21)
	v_cndmask_b32_e64 v32, v40, 0, s[0:1]
	v_cndmask_b32_e64 v19, v27, 0, s[0:1]
	v_cndmask_b32_e64 v20, v28, 0, s[0:1]
	v_cndmask_b32_e64 v21, v29, 0, s[0:1]
	v_cndmask_b32_e64 v22, v30, 0, s[0:1]
	v_cndmask_b32_e64 v23, v31, 0, s[0:1]
	v_cndmask_b32_e64 v25, v33, 0, s[0:1]
	v_cndmask_b32_e64 v26, v34, 0, s[0:1]
	v_cndmask_b32_e64 v27, v35, 0, s[0:1]
	s_waitcnt vmcnt(13)
	v_cndmask_b32_e64 v40, v52, 0, s[0:1]
	v_mul_f32_e32 v52, 0x42000000, v51
	v_mul_f32_e32 v52, 0x3fb8aa3b, v52
	v_exp_f32_e32 v158, v52
	v_add_u32_e32 v52, 17, v173
	v_cvt_f32_ubyte0_e32 v52, v52
	v_mul_f32_e32 v52, v51, v52
	v_mul_f32_e32 v52, 0x3fb8aa3b, v52
	v_exp_f32_e32 v160, v52
	v_add_u32_e32 v52, 1, v173
	v_cvt_f32_ubyte0_e32 v52, v52
	v_mul_f32_e32 v51, v51, v52
	v_mul_f32_e32 v51, 0x3fb8aa3b, v51
	v_exp_f32_e32 v162, v51
	v_mul_lo_u32 v51, v174, s54
	v_cndmask_b32_e64 v28, v36, 0, s[0:1]
	v_cndmask_b32_e64 v29, v37, 0, s[0:1]
	v_cndmask_b32_e64 v30, v38, 0, s[0:1]
	v_cndmask_b32_e64 v31, v39, 0, s[0:1]
	v_cndmask_b32_e64 v33, v41, 0, s[0:1]
	v_cndmask_b32_e64 v34, v42, 0, s[0:1]
	v_cndmask_b32_e64 v35, v43, 0, s[0:1]
	v_cndmask_b32_e64 v36, v44, 0, s[0:1]
	v_cndmask_b32_e64 v37, v45, 0, s[0:1]
	v_cndmask_b32_e64 v38, v46, 0, s[0:1]
	v_cndmask_b32_e64 v39, v47, 0, s[0:1]
	s_waitcnt vmcnt(12)
	v_cndmask_b32_e64 v41, v53, 0, s[0:1]
	s_waitcnt vmcnt(11)
	v_cndmask_b32_e64 v42, v54, 0, s[0:1]
	s_waitcnt vmcnt(10)
	v_cndmask_b32_e64 v43, v55, 0, s[0:1]
	s_waitcnt vmcnt(9)
	v_cndmask_b32_e64 v44, v56, 0, s[0:1]
	s_waitcnt vmcnt(8)
	v_cndmask_b32_e64 v45, v57, 0, s[0:1]
	s_waitcnt vmcnt(7)
	v_cndmask_b32_e64 v46, v58, 0, s[0:1]
	s_waitcnt vmcnt(6)
	v_cndmask_b32_e64 v47, v59, 0, s[0:1]
	v_add3_u32 v175, 0, v60, v51
	s_add_i32 s0, s58, -1
	v_add3_u32 v178, 0, v48, v3
	v_add3_u32 v179, 0, v3, v48
	v_mov_b32_e32 v164, v158
	v_mov_b32_e32 v165, v158
	v_mov_b32_e32 v161, v160
	v_mov_b32_e32 v166, v160
	v_mov_b32_e32 v167, v160
	v_mov_b32_e32 v163, v162
	v_mov_b32_e32 v168, v162
	v_mov_b32_e32 v169, v162
	v_lshl_add_u64 v[170:171], v[0:1], 0, v[48:49]
	v_xad_u32 v180, v173, -1, s55
	v_lshlrev_b32_e32 v181, 1, v50
	v_readlane_b32 s77, v254, 1
	v_readlane_b32 s80, v254, 4
	v_readlane_b32 s81, v254, 5
	v_readlane_b32 s82, v254, 6
	v_readlane_b32 s83, v254, 7
	s_waitcnt vmcnt(0)
.LBB0_1370:
	s_add_i32 s1, s57, -1
	s_waitcnt vmcnt(7)
	ds_write_b128 v175, v[72:75]
	ds_write_b128 v175, v[68:71] offset:8704
	ds_write_b128 v175, v[64:67] offset:17408
	v_cndmask_b32_e32 v65, v180, v173, vcc
	v_xor_b32_e32 v66, 0xffffffef, v173
	v_xor_b32_e32 v70, 0xffffffcf, v173
	s_min_u32 s18, s1, s0
	v_add_u32_e32 v69, 48, v173
	v_xor_b32_e32 v67, 0xffffffdf, v173
	v_add_u32_e32 v71, s55, v66
	v_add_u32_e32 v66, s56, v65
	v_add_u32_e32 v70, s55, v70
	v_lshl_add_u32 v73, s18, 5, v174
	v_add_u32_e32 v64, 16, v173
	v_add_u32_e32 v68, 32, v173
	v_add_u32_e32 v65, s55, v67
	v_ashrrev_i32_e32 v67, 31, v66
	v_cndmask_b32_e32 v69, v70, v69, vcc
	v_xad_u32 v70, v73, -1, s55
	v_cndmask_b32_e32 v71, v71, v64, vcc
	v_cndmask_b32_e32 v68, v65, v68, vcc
	v_lshlrev_b64 v[64:65], 11, v[66:67]
	v_cndmask_b32_e32 v67, v70, v73, vcc
	s_min_u32 s42, s57, s0
	v_lshl_add_u64 v[242:243], v[170:171], 0, v[64:65]
	v_add_u32_e32 v64, s56, v67
	v_lshl_add_u32 v72, s42, 5, v174
	v_ashrrev_i32_e32 v65, 31, v64
	v_cvt_pk_bf16_f32 v60, v44, v45
	v_cvt_pk_bf16_f32 v61, v46, v47
	v_cvt_pk_bf16_f32 v62, v40, v41
	v_cvt_pk_bf16_f32 v63, v42, v43
	v_xad_u32 v74, v72, -1, s55
	v_lshlrev_b64 v[64:65], 13, v[64:65]
	v_cndmask_b32_e32 v66, v74, v72, vcc
	v_or_b32_e32 v64, v64, v181
	v_add_u32_e32 v238, s56, v68
	v_add_u32_e32 v240, s56, v69
	v_add_u32_e32 v244, s56, v66
	v_lshl_add_u64 v[66:67], s[36:37], 0, v[64:65]
	v_lshl_add_u64 v[68:69], s[38:39], 0, v[64:65]
	v_lshl_add_u64 v[64:65], s[40:41], 0, v[64:65]
	v_add_u32_e32 v0, 0x1000, v178
	v_add_u32_e32 v1, 0x2000, v179
	v_add_u32_e32 v182, 0x3000, v179
	v_add_u32_e32 v236, s56, v71
	global_load_dwordx4 v[72:75], v[66:67], off
	s_nop 0
	global_load_dwordx4 v[68:71], v[68:69], off
	s_nop 0
	global_load_dwordx4 v[64:67], v[64:65], off
	s_waitcnt lgkmcnt(0)
	s_barrier
	ds_read2_b64 v[188:191], v178 offset1:4
	ds_read2_b64 v[192:195], v0 offset0:32 offset1:36
	ds_read2_b64 v[196:199], v0 offset0:40 offset1:44
	ds_read2_b64 v[200:203], v1 offset0:64 offset1:68
	ds_read2_b64 v[204:207], v182 offset0:96 offset1:100
	ds_read_b64_tr_b16 v[210:211], v176 offset:13056
	ds_read_b64_tr_b16 v[212:213], v177 offset:17408
	ds_read_b64_tr_b16 v[214:215], v177 offset:21760
	ds_read_b64_tr_b16 v[208:209], v176 offset:8704
	ds_read_b64_tr_b16 v[216:217], v176 offset:8736
	ds_read_b64_tr_b16 v[220:221], v176 offset:8768
	ds_read_b64_tr_b16 v[222:223], v176 offset:13120
	ds_read_b64_tr_b16 v[218:219], v176 offset:13088
	ds_read_b64_tr_b16 v[230:231], v176 offset:8928
	s_waitcnt lgkmcnt(7)
	v_lshlrev_b32_e32 v232, 16, v212
	v_and_b32_e32 v233, 0xffff0000, v212
	v_lshlrev_b32_e32 v234, 16, v213
	v_and_b32_e32 v235, 0xffff0000, v213
	s_waitcnt lgkmcnt(6)
	v_lshlrev_b32_e32 v246, 16, v214
	v_and_b32_e32 v247, 0xffff0000, v214
	v_lshlrev_b32_e32 v248, 16, v215
	v_and_b32_e32 v249, 0xffff0000, v215
	v_mov_b32_e32 v159, v158
	v_mfma_f32_16x16x32_bf16 v[226:229], v[60:63], v[192:195], 0
	v_mul_f32_e64 v232, v150, v232
	v_mul_f32_e64 v233, v151, v233
	v_pk_mul_f32 v[234:235], v[152:153], v[234:235]
	v_pk_mul_f32 v[44:45], v[164:165], v[44:45]
	v_mfma_f32_16x16x32_bf16 v[60:63], v[60:63], v[188:191], 0
	v_mul_f32_e64 v46, v158, v46
	v_mul_f32_e64 v47, v159, v47
	v_pk_mul_f32 v[40:41], v[164:165], v[40:41]
	v_pk_mul_f32 v[42:43], v[158:159], v[42:43]
	v_mfma_f32_16x16x32_bf16 v[188:191], v[200:203], v[188:191], 0
	v_cvt_pk_bf16_f32 v52, v36, v37
	v_cvt_pk_bf16_f32 v53, v38, v39
	v_cvt_pk_bf16_f32 v54, v32, v33
	v_mfma_f32_16x16x32_bf16 v[200:203], v[200:203], v[192:195], 0
	v_cvt_pk_bf16_f32 v55, v34, v35
	v_cvt_pk_bf16_f32 v56, v28, v29
	v_cvt_pk_bf16_f32 v57, v30, v31
	v_mfma_f32_16x16x32_bf16 v[192:195], v[204:207], v[192:195], 0
	v_mul_f32_e64 v206, v154, v246
	v_mul_f32_e64 v207, v155, v247
	v_pk_mul_f32 v[246:247], v[156:157], v[248:249]
	v_cvt_pk_bf16_f32 v204, v232, v233
	v_cvt_pk_bf16_f32 v205, v234, v235
	v_cvt_pk_bf16_f32 v206, v206, v207
	v_cvt_pk_bf16_f32 v207, v246, v247
	v_pk_mul_f32 v[36:37], v[164:165], v[36:37]
	v_pk_mul_f32 v[32:33], v[164:165], v[32:33]
	s_waitcnt lgkmcnt(5)
	v_mfma_f32_16x16x32_bf16 v[44:47], v[208:211], v[204:207], v[44:47]
	ds_read_b64_tr_b16 v[210:211], v176 offset:13152
	ds_read_b64_tr_b16 v[208:209], v176 offset:8800
	ds_read_b64_tr_b16 v[232:233], v176 offset:8832
	v_pk_mul_f32 v[28:29], v[164:165], v[28:29]
	v_pk_mul_f32 v[38:39], v[158:159], v[38:39]
	s_waitcnt lgkmcnt(4)
	v_mfma_f32_16x16x32_bf16 v[40:43], v[216:219], v[204:207], v[40:43]
	ds_read_b64_tr_b16 v[216:217], v176 offset:8864
	ds_read_b64_tr_b16 v[234:235], v176 offset:13184
	ds_read_b64_tr_b16 v[218:219], v176 offset:13216
	v_pk_mul_f32 v[34:35], v[158:159], v[34:35]
	v_pk_mul_f32 v[30:31], v[158:159], v[30:31]
	v_mfma_f32_16x16x32_bf16 v[36:39], v[220:223], v[204:207], v[36:39]
	v_ashrrev_i32_e32 v245, 31, v244
	v_ashrrev_i32_e32 v237, 31, v236
	v_cvt_pk_bf16_f32 v58, v24, v25
	s_waitcnt lgkmcnt(4)
	v_mfma_f32_16x16x32_bf16 v[32:35], v[208:211], v[204:207], v[32:35]
	ds_read_b64_tr_b16 v[208:209], v176 offset:8896
	ds_read_b64_tr_b16 v[210:211], v176 offset:13248
	v_cvt_pk_bf16_f32 v59, v26, v27
	s_waitcnt lgkmcnt(3)
	v_mfma_f32_16x16x32_bf16 v[220:223], v[232:235], v[204:207], v[28:31]
	ds_read_b64_tr_b16 v[232:233], v176 offset:13280
	v_cvt_pk_bf16_f32 v48, v20, v21
	v_cvt_pk_bf16_f32 v49, v22, v23
	v_lshlrev_b64 v[28:29], 13, v[244:245]
	v_cvt_pk_bf16_f32 v50, v16, v17
	v_cvt_pk_bf16_f32 v51, v18, v19
	v_pk_mul_f32 v[24:25], v[164:165], v[24:25]
	v_pk_mul_f32 v[20:21], v[164:165], v[20:21]
	v_pk_mul_f32 v[16:17], v[164:165], v[16:17]
	v_pk_mul_f32 v[26:27], v[158:159], v[26:27]
	v_pk_mul_f32 v[22:23], v[158:159], v[22:23]
	v_pk_mul_f32 v[18:19], v[158:159], v[18:19]
	v_ashrrev_i32_e32 v239, 31, v238
	v_ashrrev_i32_e32 v241, 31, v240
	v_lshlrev_b64 v[236:237], 11, v[236:237]
	v_or_b32_e32 v28, v28, v181
	v_lshlrev_b64 v[246:247], 11, v[238:239]
	v_lshlrev_b64 v[248:249], 11, v[240:241]
	s_waitcnt lgkmcnt(3)
	v_mfma_f32_16x16x32_bf16 v[216:219], v[216:219], v[204:207], v[24:27]
	v_lshl_add_u64 v[234:235], v[170:171], 0, v[236:237]
	v_lshl_add_u64 v[236:237], s[36:37], 0, v[28:29]
	v_lshl_add_u64 v[238:239], s[38:39], 0, v[28:29]
	s_waitcnt lgkmcnt(1)
	v_mfma_f32_16x16x32_bf16 v[208:211], v[208:211], v[204:207], v[20:23]
	ds_read2_b64 v[24:27], v1 offset0:72 offset1:76
	v_lshl_add_u64 v[240:241], s[40:41], 0, v[28:29]
	ds_read2_b64 v[28:31], v182 offset0:104 offset1:108
	s_waitcnt lgkmcnt(2)
	v_mfma_f32_16x16x32_bf16 v[204:207], v[230:233], v[204:207], v[16:19]
	v_mov_b32_e32 v3, v2
	v_add_u32_e32 v183, 0x6000, v178
	v_add_u32_e32 v184, 0x7000, v178
	ds_read2_b64 v[16:19], v178 offset0:8 offset1:12
	v_mfma_f32_16x16x32_bf16 v[226:229], v[52:55], v[196:199], v[226:229]
	v_add_u32_e32 v185, 0x8800, v179
	v_add_u32_e32 v186, 0x9800, v179
	s_add_i32 s57, s57, 2
	s_waitcnt lgkmcnt(0)
	v_mfma_f32_16x16x32_bf16 v[20:23], v[52:55], v[16:19], v[60:63]
	ds_read2_b64 v[52:55], v0 offset0:48 offset1:52
	s_nop 1
	ds_read2_b64 v[60:63], v178 offset0:16 offset1:20
	v_add_u32_e32 v173, 64, v173
	v_subrev_u32_e32 v180, 64, v180
	v_mfma_f32_16x16x32_bf16 v[16:19], v[24:27], v[16:19], v[188:191]
	s_cmp_ge_u32 s1, s58
	v_mfma_f32_16x16x32_bf16 v[24:27], v[24:27], v[196:199], v[200:203]
	v_mfma_f32_16x16x32_bf16 v[28:31], v[28:31], v[196:199], v[192:195]
	s_nop 2
	ds_read2_b64 v[192:195], v1 offset0:80 offset1:84
	ds_read2_b64 v[196:199], v178 offset0:24 offset1:28
	ds_read2_b64 v[200:203], v0 offset0:56 offset1:60
	s_waitcnt lgkmcnt(4)
	v_mfma_f32_16x16x32_bf16 v[188:191], v[56:59], v[52:55], v[226:229]
	s_waitcnt lgkmcnt(3)
	v_mfma_f32_16x16x32_bf16 v[20:23], v[56:59], v[60:63], v[20:23]
	ds_read2_b64 v[56:59], v182 offset0:112 offset1:116
	ds_read2_b64 v[226:229], v1 offset0:88 offset1:92
	ds_read2_b64 v[230:233], v182 offset0:120 offset1:124
	s_waitcnt vmcnt(5)
	ds_write_b128 v175, v[12:15] offset:26112
	ds_write_b128 v175, v[8:11] offset:34816
	ds_write_b128 v175, v[4:7] offset:43520
	s_waitcnt lgkmcnt(8)
	v_mfma_f32_16x16x32_bf16 v[16:19], v[192:195], v[60:63], v[16:19]
	v_mfma_f32_16x16x32_bf16 v[4:7], v[192:195], v[52:55], v[24:27]
	s_waitcnt lgkmcnt(5)
	v_mfma_f32_16x16x32_bf16 v[8:11], v[56:59], v[52:55], v[28:31]
	s_nop 0
	v_cvt_pk_bf16_f32 v24, v44, v45
	v_cvt_pk_bf16_f32 v25, v46, v47
	v_cvt_pk_bf16_f32 v26, v40, v41
	s_waitcnt lgkmcnt(4)
	v_mfma_f32_16x16x32_bf16 v[16:19], v[226:229], v[196:199], v[16:19]
	v_mul_f32_e64 v28, v164, v44
	v_mul_f32_e64 v29, v165, v45
	v_cvt_pk_bf16_f32 v27, v42, v43
	v_pk_mul_f32 v[30:31], v[158:159], v[46:47]
	v_mfma_f32_16x16x32_bf16 v[4:7], v[226:229], v[200:203], v[4:7]
	v_cvt_pk_bf16_f32 v52, v36, v37
	s_nop 1
	v_pk_mul_f32 v[18:19], v[146:147], v[18:19]
	v_pk_mul_f32 v[0:1], v[142:143], v[16:17]
	s_waitcnt lgkmcnt(3)
	v_mfma_f32_16x16x32_bf16 v[8:11], v[230:233], v[200:203], v[8:11]
	v_cvt_pk_bf16_f32 v0, v0, v1
	v_pk_mul_f32 v[6:7], v[148:149], v[6:7]
	v_pk_mul_f32 v[4:5], v[144:145], v[4:5]
	v_cvt_pk_bf16_f32 v1, v18, v19
	v_cvt_pk_bf16_f32 v4, v4, v5
	s_nop 2
	v_pk_mul_f32 v[16:17], v[146:147], v[10:11]
	v_pk_mul_f32 v[44:45], v[142:143], v[8:9]
	v_cvt_pk_bf16_f32 v5, v6, v7
	v_cvt_pk_bf16_f32 v6, v44, v45
	v_cvt_pk_bf16_f32 v7, v16, v17
	v_mfma_f32_16x16x32_bf16 v[12:15], v[48:51], v[200:203], v[188:191]
	v_cvt_pk_bf16_f32 v53, v38, v39
	v_pk_mul_f32 v[38:39], v[158:159], v[38:39]
	v_pk_mul_f32 v[36:37], v[164:165], v[36:37]
	v_mfma_f32_16x16x32_bf16 v[20:23], v[48:51], v[196:199], v[20:23]
	v_cvt_pk_bf16_f32 v54, v32, v33
	v_cvt_pk_bf16_f32 v55, v34, v35
	v_pk_mul_f32 v[42:43], v[158:159], v[42:43]
	v_mfma_f32_16x16x32_bf16 v[8:11], v[212:215], v[0:3], 0
	v_mul_f32_e64 v40, v164, v40
	v_mul_f32_e64 v41, v165, v41
	v_pk_mul_f32 v[34:35], v[158:159], v[34:35]
	v_pk_mul_f32 v[32:33], v[164:165], v[32:33]
	v_mfma_f32_16x16x32_bf16 v[4:7], v[212:215], v[4:7], 0
	v_mul_f32_e64 v50, v158, v222
	v_mul_f32_e64 v51, v159, v223
	s_nop 0
	v_pk_fma_f32 v[8:9], v[162:163], v[20:21], v[8:9]
	v_pk_mul_f32 v[48:49], v[164:165], v[220:221]
	v_cvt_pk_bf16_f32 v8, v8, v9
	v_cvt_pk_bf16_f32 v56, v220, v221
	s_nop 0
	v_pk_fma_f32 v[0:1], v[166:167], v[14:15], v[6:7]
	v_pk_fma_f32 v[6:7], v[168:169], v[22:23], v[10:11]
	v_pk_fma_f32 v[4:5], v[160:161], v[12:13], v[4:5]
	v_cvt_pk_bf16_f32 v9, v6, v7
	v_cvt_pk_bf16_f32 v4, v4, v5
	v_cvt_pk_bf16_f32 v5, v0, v1
	global_store_dwordx2 v[242:243], v[8:9], off
	global_store_dwordx2 v[234:235], v[4:5], off
	global_load_dwordx4 v[12:15], v[236:237], off
	s_nop 0
	global_load_dwordx4 v[8:11], v[238:239], off
	global_load_dwordx4 v[4:7], v[240:241], off
	s_waitcnt lgkmcnt(0)
	s_barrier
	ds_read2_b64 v[16:19], v183 offset0:192 offset1:196
	ds_read2_b64 v[20:23], v184 offset0:224 offset1:228
	ds_read2_b64 v[60:63], v184 offset0:232 offset1:236
	ds_read2_b64 v[44:47], v185 offset1:4
	ds_read2_b64 v[188:191], v186 offset0:32 offset1:36
	ds_read_b64_tr_b16 v[194:195], v176 offset:39168
	ds_read_b64_tr_b16 v[196:197], v177 offset:43520
	ds_read_b64_tr_b16 v[198:199], v177 offset:47872
	ds_read_b64_tr_b16 v[192:193], v176 offset:34816
	ds_read_b64_tr_b16 v[200:201], v176 offset:34848
	ds_read_b64_tr_b16 v[212:213], v176 offset:34880
	ds_read_b64_tr_b16 v[214:215], v176 offset:39232
	s_waitcnt lgkmcnt(10)
	v_mfma_f32_16x16x32_bf16 v[226:229], v[24:27], v[20:23], 0
	s_waitcnt lgkmcnt(5)
	v_lshlrev_b32_e32 v0, 16, v196
	v_and_b32_e32 v1, 0xffff0000, v196
	v_pk_mul_f32 v[0:1], v[150:151], v[0:1]
	v_mfma_f32_16x16x32_bf16 v[234:237], v[24:27], v[16:19], 0
	v_lshlrev_b32_e32 v24, 16, v197
	v_and_b32_e32 v25, 0xffff0000, v197
	v_pk_mul_f32 v[24:25], v[152:153], v[24:25]
	v_mfma_f32_16x16x32_bf16 v[238:241], v[44:47], v[16:19], 0
	s_waitcnt lgkmcnt(4)
	v_lshlrev_b32_e32 v16, 16, v198
	v_and_b32_e32 v17, 0xffff0000, v198
	v_lshlrev_b32_e32 v18, 16, v199
	v_and_b32_e32 v19, 0xffff0000, v199
	v_mfma_f32_16x16x32_bf16 v[242:245], v[44:47], v[20:23], 0
	ds_read_b64_tr_b16 v[202:203], v176 offset:39200
	ds_read_b64_tr_b16 v[230:231], v176 offset:35040
	v_cvt_pk_bf16_f32 v57, v222, v223
	v_cvt_pk_bf16_f32 v58, v216, v217
	v_mfma_f32_16x16x32_bf16 v[188:191], v[188:191], v[20:23], 0
	v_mul_f32_e64 v20, v154, v16
	v_mul_f32_e64 v21, v155, v17
	v_pk_mul_f32 v[22:23], v[156:157], v[18:19]
	v_cvt_pk_bf16_f32 v16, v0, v1
	v_cvt_pk_bf16_f32 v17, v24, v25
	v_cvt_pk_bf16_f32 v18, v20, v21
	v_cvt_pk_bf16_f32 v19, v22, v23
	ds_read_b64_tr_b16 v[22:23], v176 offset:39264
	ds_read_b64_tr_b16 v[20:21], v176 offset:34912
	ds_read_b64_tr_b16 v[24:25], v176 offset:34944
	s_waitcnt lgkmcnt(8)
	v_mfma_f32_16x16x32_bf16 v[44:47], v[192:195], v[16:19], v[28:31]
	ds_read_b64_tr_b16 v[192:193], v176 offset:34976
	ds_read_b64_tr_b16 v[26:27], v176 offset:39296
	ds_read_b64_tr_b16 v[194:195], v176 offset:39328
	ds_read_b64_tr_b16 v[232:233], v176 offset:39392
	v_cvt_pk_bf16_f32 v59, v218, v219
	s_waitcnt lgkmcnt(9)
	v_mfma_f32_16x16x32_bf16 v[36:39], v[212:215], v[16:19], v[36:39]
	ds_read_b64_tr_b16 v[212:213], v176 offset:35008
	ds_read_b64_tr_b16 v[214:215], v176 offset:39360
	s_waitcnt lgkmcnt(10)
	v_mfma_f32_16x16x32_bf16 v[40:43], v[200:203], v[16:19], v[40:43]
	v_mul_f32_e64 v202, v158, v218
	v_mul_f32_e64 v203, v159, v219
	v_pk_mul_f32 v[200:201], v[164:165], v[216:217]
	ds_read2_b64 v[216:219], v183 offset0:208 offset1:212
	s_waitcnt lgkmcnt(8)
	v_mfma_f32_16x16x32_bf16 v[32:35], v[20:23], v[16:19], v[32:35]
	v_mul_f32_e64 v22, v158, v210
	v_mul_f32_e64 v23, v159, v211
	v_pk_mul_f32 v[20:21], v[164:165], v[208:209]
	s_waitcnt lgkmcnt(5)
	v_mfma_f32_16x16x32_bf16 v[28:31], v[24:27], v[16:19], v[48:51]
	s_waitcnt lgkmcnt(4)
	v_mfma_f32_16x16x32_bf16 v[24:27], v[192:195], v[16:19], v[200:203]
	ds_read2_b64 v[192:195], v185 offset0:8 offset1:12
	v_pk_mul_f32 v[50:51], v[158:159], v[206:207]
	v_pk_mul_f32 v[48:49], v[164:165], v[204:205]
	s_waitcnt lgkmcnt(2)
	v_mfma_f32_16x16x32_bf16 v[20:23], v[212:215], v[16:19], v[20:23]
	ds_read2_b64 v[212:215], v186 offset0:40 offset1:44
	v_cvt_pk_bf16_f32 v202, v204, v205
	v_cvt_pk_bf16_f32 v203, v206, v207
	v_mfma_f32_16x16x32_bf16 v[16:19], v[230:233], v[16:19], v[48:51]
	ds_read2_b64 v[204:207], v183 offset0:216 offset1:220
	v_cvt_pk_bf16_f32 v200, v208, v209
	v_cvt_pk_bf16_f32 v201, v210, v211
	ds_read2_b64 v[48:51], v183 offset0:200 offset1:204
	v_mfma_f32_16x16x32_bf16 v[226:229], v[52:55], v[60:63], v[226:229]
	s_waitcnt lgkmcnt(0)
	v_mfma_f32_16x16x32_bf16 v[52:55], v[52:55], v[48:51], v[234:237]
	v_mfma_f32_16x16x32_bf16 v[48:51], v[192:195], v[48:51], v[238:241]
	v_mfma_f32_16x16x32_bf16 v[192:195], v[192:195], v[60:63], v[242:245]
	v_mfma_f32_16x16x32_bf16 v[60:63], v[212:215], v[60:63], v[188:191]
	s_nop 2
	ds_read2_b64 v[188:191], v184 offset0:240 offset1:244
	s_waitcnt lgkmcnt(0)
	v_mfma_f32_16x16x32_bf16 v[212:215], v[56:59], v[188:191], v[226:229]
	v_mfma_f32_16x16x32_bf16 v[52:55], v[56:59], v[216:219], v[52:55]
	ds_read2_b64 v[56:59], v185 offset0:16 offset1:20
	s_waitcnt lgkmcnt(0)
	v_mfma_f32_16x16x32_bf16 v[48:51], v[56:59], v[216:219], v[48:51]
	v_mfma_f32_16x16x32_bf16 v[56:59], v[56:59], v[188:191], v[192:195]
	s_nop 2
	ds_read2_b64 v[192:195], v186 offset0:48 offset1:52
	s_waitcnt lgkmcnt(0)
	v_mfma_f32_16x16x32_bf16 v[60:63], v[192:195], v[188:191], v[60:63]
	ds_read2_b64 v[188:191], v184 offset0:248 offset1:252
	ds_read2_b64 v[182:185], v185 offset0:24 offset1:28
	s_waitcnt lgkmcnt(0)
	v_mfma_f32_16x16x32_bf16 v[48:51], v[182:185], v[204:207], v[48:51]
	s_nop 7
	v_pk_mul_f32 v[50:51], v[146:147], v[50:51]
	v_mfma_f32_16x16x32_bf16 v[56:59], v[182:185], v[188:191], v[56:59]
	ds_read2_b64 v[182:185], v186 offset0:56 offset1:60
	v_pk_mul_f32 v[0:1], v[142:143], v[48:49]
	s_waitcnt lgkmcnt(0)
	v_mfma_f32_16x16x32_bf16 v[60:63], v[182:185], v[188:191], v[60:63]
	s_nop 3
	v_mul_f32_e64 v182, v148, v58
	v_mul_f32_e64 v183, v149, v59
	v_pk_mul_f32 v[48:49], v[144:145], v[56:57]
	v_cvt_pk_bf16_f32 v0, v0, v1
	v_pk_mul_f32 v[62:63], v[146:147], v[62:63]
	v_pk_mul_f32 v[60:61], v[142:143], v[60:61]
	v_cvt_pk_bf16_f32 v1, v50, v51
	v_cvt_pk_bf16_f32 v48, v48, v49
	v_cvt_pk_bf16_f32 v49, v182, v183
	v_cvt_pk_bf16_f32 v50, v60, v61
	v_cvt_pk_bf16_f32 v51, v62, v63
	v_mfma_f32_16x16x32_bf16 v[192:195], v[200:203], v[188:191], v[212:215]
	v_mfma_f32_16x16x32_bf16 v[52:55], v[200:203], v[204:207], v[52:55]
	v_lshl_add_u64 v[200:201], v[170:171], 0, v[246:247]
	v_lshl_add_u64 v[202:203], v[170:171], 0, v[248:249]
	v_mfma_f32_16x16x32_bf16 v[56:59], v[196:199], v[0:3], 0
	v_mfma_f32_16x16x32_bf16 v[48:51], v[196:199], v[48:51], 0
	s_nop 6
	v_fma_f32 v52, v162, v52, v56
	v_fma_f32 v53, v163, v53, v57
	v_pk_fma_f32 v[0:1], v[166:167], v[194:195], v[50:51]
	v_pk_fma_f32 v[50:51], v[168:169], v[54:55], v[58:59]
	v_pk_fma_f32 v[48:49], v[160:161], v[192:193], v[48:49]
	v_cvt_pk_bf16_f32 v52, v52, v53
	v_cvt_pk_bf16_f32 v53, v50, v51
	v_cvt_pk_bf16_f32 v48, v48, v49
	v_cvt_pk_bf16_f32 v49, v0, v1
	global_store_dwordx2 v[200:201], v[52:53], off
	global_store_dwordx2 v[202:203], v[48:49], off
	s_cbranch_scc0 .LBB0_1370
	s_andn2_b64 vcc, exec, s[6:7]
	s_cbranch_vccnz .LBB0_1354
	s_add_u32 s0, s28, s14
	s_addc_u32 s1, s29, s15
	v_lshl_add_u64 v[0:1], v[112:113], 2, s[0:1]
	s_waitcnt vmcnt(2)
	v_lshl_add_u64 v[4:5], v[0:1], 0, v[76:77]
	global_store_dword v[4:5], v44, off nt
	v_lshl_add_u64 v[4:5], v[0:1], 0, v[78:79]
	global_store_dword v[4:5], v45, off nt
	v_lshl_add_u64 v[4:5], v[0:1], 0, v[80:81]
	global_store_dword v[4:5], v46, off nt
	v_lshl_add_u64 v[4:5], v[0:1], 0, v[82:83]
	global_store_dword v[4:5], v47, off nt
	v_lshl_add_u64 v[4:5], v[0:1], 0, v[84:85]
	global_store_dword v[4:5], v40, off nt
	v_lshl_add_u64 v[4:5], v[0:1], 0, v[86:87]
	global_store_dword v[4:5], v41, off nt
	v_lshl_add_u64 v[4:5], v[0:1], 0, v[88:89]
	global_store_dword v[4:5], v42, off nt
	v_lshl_add_u64 v[4:5], v[0:1], 0, v[90:91]
	global_store_dword v[4:5], v43, off nt
	v_lshl_add_u64 v[4:5], v[0:1], 0, v[92:93]
	global_store_dword v[4:5], v36, off nt
	v_lshl_add_u64 v[4:5], v[0:1], 0, v[94:95]
	global_store_dword v[4:5], v37, off nt
	v_lshl_add_u64 v[4:5], v[0:1], 0, v[96:97]
	global_store_dword v[4:5], v38, off nt
	v_lshl_add_u64 v[4:5], v[0:1], 0, v[98:99]
	global_store_dword v[4:5], v39, off nt
	v_lshl_add_u64 v[4:5], v[0:1], 0, v[100:101]
	global_store_dword v[4:5], v32, off nt
	v_lshl_add_u64 v[4:5], v[0:1], 0, v[102:103]
	global_store_dword v[4:5], v33, off nt
	v_lshl_add_u64 v[4:5], v[0:1], 0, v[104:105]
	global_store_dword v[4:5], v34, off nt
	v_lshl_add_u64 v[4:5], v[0:1], 0, v[106:107]
	global_store_dword v[4:5], v35, off nt
	v_lshl_add_u64 v[4:5], v[0:1], 0, v[108:109]
	global_store_dword v[4:5], v28, off nt
	v_lshl_add_u64 v[4:5], v[0:1], 0, v[110:111]
	global_store_dword v[4:5], v29, off nt
	v_lshl_add_u64 v[4:5], v[0:1], 0, v[138:139]
	global_store_dword v[4:5], v30, off nt
	v_lshl_add_u64 v[4:5], v[0:1], 0, v[136:137]
	global_store_dword v[4:5], v31, off nt
	v_lshl_add_u64 v[4:5], v[0:1], 0, v[134:135]
	global_store_dword v[4:5], v24, off nt
	v_lshl_add_u64 v[4:5], v[0:1], 0, v[132:133]
	global_store_dword v[4:5], v25, off nt
	v_lshl_add_u64 v[4:5], v[0:1], 0, v[130:131]
	global_store_dword v[4:5], v26, off nt
	v_lshl_add_u64 v[4:5], v[0:1], 0, v[128:129]
	global_store_dword v[4:5], v27, off nt
	v_lshl_add_u64 v[4:5], v[0:1], 0, v[126:127]
	global_store_dword v[4:5], v20, off nt
	v_lshl_add_u64 v[4:5], v[0:1], 0, v[124:125]
	global_store_dword v[4:5], v21, off nt
	v_lshl_add_u64 v[4:5], v[0:1], 0, v[122:123]
	global_store_dword v[4:5], v22, off nt
	v_lshl_add_u64 v[4:5], v[0:1], 0, v[120:121]
	global_store_dword v[4:5], v23, off nt
	v_lshl_add_u64 v[4:5], v[0:1], 0, v[118:119]
	global_store_dword v[4:5], v16, off nt
	v_lshl_add_u64 v[4:5], v[0:1], 0, v[116:117]
	global_store_dword v[4:5], v17, off nt
	v_lshl_add_u64 v[4:5], v[0:1], 0, v[114:115]
	v_lshl_add_u64 v[0:1], v[0:1], 0, v[140:141]
	global_store_dword v[4:5], v18, off nt
	global_store_dword v[0:1], v19, off nt
	s_branch .LBB0_1354
